# DPP wave reductions: first four butterfly hops (lane^1,^2,^4,^8) of every 64-lane sum in the row-wise phases (W0 prep/norm rows, E1 x2, E2 x3, final norm) as v_mov_b32_dpp quad_perm/row_half_mirror/ro
# speedup vs baseline: 1.0029x; 1.0029x over previous
; __device__ __forceinline__ unsigned cvt_pk_bf16(float lo, float hi) { unsigned r; asm volatile("v_cvt_pk_bf16_f32 %0, %1, %2" : "=v"(r) : "v"(lo), "v"(hi)); return r; }
; __device__ __forceinline__ float wave_sum(float v, int lane) {
; #pragma unroll
;     for (int o = 1; o < 64; o <<= 1) v += __uint_as_float((unsigned)__builtin_amdgcn_ds_bpermute((lane ^ o) << 2, (int)__float_as_uint(v)));
;     return v;
; }
; __device__ __forceinline__ void prep_row(const float* xrow, bf16_t* orow, float* ssq, float* rsb, int m, int lane) {
;     const f32x4* xr = (const f32x4*)xrow + lane; f32x4 v[8]; float s = 0.f;
; #pragma unroll
;     for (int j = 0; j < 8; ++j) { v[j] = xr[64 * j]; s += (v[j].x * v[j].x + v[j].y * v[j].y) + (v[j].z * v[j].z + v[j].w * v[j].w); }
;     const float tot = wave_sum(s, lane);
;     u32x2* o8 = (u32x2*)orow + lane;
; #pragma unroll
;     for (int j = 0; j < 8; ++j) { u32x2 w; w.x = cvt_pk_bf16(v[j].x, v[j].y); w.y = cvt_pk_bf16(v[j].z, v[j].w); o8[64 * j] = w; }
;     if (lane < 32) ssq[(size_t)lane * MTOK + m] = (lane == 0) ? tot : 0.f;
;     if (lane == 0) rsb[m] = rsqrtf(tot * (1.f / 2048.f) + EPS);
; }
.LBB0_184:
	global_load_dwordx4 v[16:19], v194, s[60:61]
	global_load_dwordx4 v[20:23], v194, s[60:61] offset:1024
	global_load_dwordx4 v[24:27], v194, s[60:61] offset:2048
	global_load_dwordx4 v[28:31], v194, s[60:61] offset:3072
	v_lshl_add_u64 v[32:33], s[60:61], 0, v[194:195]
	s_movk_i32 s49, 0x1000
	v_add_co_u32_e32 v44, vcc, s49, v32
	s_lshl_b64 s[60:61], s[58:59], 12
	s_nop 0
	v_addc_co_u32_e32 v45, vcc, 0, v33, vcc
	global_load_dwordx4 v[32:35], v[44:45], off
	global_load_dwordx4 v[36:39], v[44:45], off offset:1024
	global_load_dwordx4 v[40:43], v[44:45], off offset:2048
	s_nop 0
	global_load_dwordx4 v[44:47], v[44:45], off offset:3072
	s_waitcnt vmcnt(7)
	v_mul_f32_e32 v11, v17, v17
	v_mul_f32_e32 v13, v19, v19
	s_waitcnt vmcnt(6)
	v_mul_f32_e32 v14, v21, v21
	v_mul_f32_e32 v48, v23, v23
	s_waitcnt vmcnt(5)
	v_mul_f32_e32 v49, v25, v25
	v_mul_f32_e32 v50, v27, v27
	v_fmac_f32_e32 v11, v16, v16
	v_fmac_f32_e32 v13, v18, v18
	v_fmac_f32_e32 v14, v20, v20
	v_fmac_f32_e32 v48, v22, v22
	s_waitcnt vmcnt(4)
	v_mul_f32_e32 v51, v29, v29
	v_mul_f32_e32 v52, v31, v31
	v_fmac_f32_e32 v49, v24, v24
	v_fmac_f32_e32 v50, v26, v26
	v_add_f32_e32 v11, v11, v13
	v_add_f32_e32 v13, v14, v48
	v_fmac_f32_e32 v51, v28, v28
	v_fmac_f32_e32 v52, v30, v30
	v_add_f32_e32 v14, v49, v50
	s_waitcnt vmcnt(3)
	v_mul_f32_e32 v49, v33, v33
	v_mul_f32_e32 v50, v35, v35
	v_add_f32_e32 v11, v11, v13
	v_add_f32_e32 v48, v51, v52
	s_waitcnt vmcnt(2)
	v_mul_f32_e32 v51, v37, v37
	v_mul_f32_e32 v52, v39, v39
	v_fmac_f32_e32 v49, v32, v32
	v_fmac_f32_e32 v50, v34, v34
	v_add_f32_e32 v11, v11, v14
	s_waitcnt vmcnt(1)
	v_mul_f32_e32 v53, v41, v41
	v_mul_f32_e32 v54, v43, v43
	v_fmac_f32_e32 v51, v36, v36
	v_fmac_f32_e32 v52, v38, v38
	v_add_f32_e32 v13, v49, v50
	v_add_f32_e32 v11, v11, v48
	s_waitcnt vmcnt(0)
	v_mul_f32_e32 v55, v45, v45
	v_mul_f32_e32 v56, v47, v47
	v_fmac_f32_e32 v53, v40, v40
	v_fmac_f32_e32 v54, v42, v42
	v_add_f32_e32 v14, v51, v52
	v_add_f32_e32 v11, v11, v13
	v_fmac_f32_e32 v55, v44, v44
	v_fmac_f32_e32 v56, v46, v46
	v_add_f32_e32 v49, v53, v54
	v_add_f32_e32 v11, v11, v14
	v_add_f32_e32 v50, v55, v56
	v_add_f32_e32 v11, v11, v49
	v_add_f32_e32 v11, v11, v50
	s_nop 1
	v_mov_b32_dpp v13, v11 quad_perm:[1,0,3,2] row_mask:0xf bank_mask:0xf
	v_lshl_add_u64 v[48:49], v[0:1], 0, s[60:61]
	v_cvt_pk_bf16_f32 v16, v16, v17
	v_cvt_pk_bf16_f32 v17, v18, v19
	global_store_dwordx2 v[48:49], v[16:17], off
	s_waitcnt lgkmcnt(0)
	v_add_f32_e32 v11, v11, v13
	s_nop 1
	v_mov_b32_dpp v13, v11 quad_perm:[2,3,0,1] row_mask:0xf bank_mask:0xf
	v_cvt_pk_bf16_f32 v16, v20, v21
	v_cvt_pk_bf16_f32 v17, v22, v23
	global_store_dwordx2 v[48:49], v[16:17], off offset:512
	v_cvt_pk_bf16_f32 v16, v24, v25
	s_waitcnt lgkmcnt(0)
	v_add_f32_e32 v11, v11, v13
	s_nop 1
	v_mov_b32_dpp v13, v11 row_half_mirror row_mask:0xf bank_mask:0xf
	v_cvt_pk_bf16_f32 v17, v26, v27
	global_store_dwordx2 v[48:49], v[16:17], off offset:1024
	v_cvt_pk_bf16_f32 v16, v28, v29
	v_cvt_pk_bf16_f32 v17, v30, v31
	s_waitcnt lgkmcnt(0)
	v_add_f32_e32 v11, v11, v13
	s_nop 1
	v_mov_b32_dpp v13, v11 row_mirror row_mask:0xf bank_mask:0xf
	global_store_dwordx2 v[48:49], v[16:17], off offset:1536
	v_cvt_pk_bf16_f32 v16, v32, v33
	v_cvt_pk_bf16_f32 v17, v34, v35
	global_store_dwordx2 v[48:49], v[16:17], off offset:2048
	s_waitcnt lgkmcnt(0)
	v_add_f32_e32 v11, v11, v13
	ds_bpermute_b32 v13, v9, v11
	v_cvt_pk_bf16_f32 v16, v36, v37
	v_cvt_pk_bf16_f32 v17, v38, v39
	global_store_dwordx2 v[48:49], v[16:17], off offset:2560
	v_cvt_pk_bf16_f32 v16, v40, v41
	s_waitcnt lgkmcnt(0)
	v_add_f32_e32 v11, v11, v13
	ds_bpermute_b32 v13, v12, v11
	v_cvt_pk_bf16_f32 v17, v42, v43
	global_store_dwordx2 v[48:49], v[16:17], off offset:3072
	v_cvt_pk_bf16_f32 v16, v44, v45
	v_cvt_pk_bf16_f32 v17, v46, v47
	s_waitcnt lgkmcnt(0)
	v_add_f32_e32 v11, v11, v13
	global_store_dwordx2 v[48:49], v[16:17], off offset:3584
	s_and_saveexec_b64 s[60:61], s[36:37]
	s_cbranch_execz .LBB0_186
	v_cndmask_b32_e64 v13, 0, v11, s[38:39]
	v_lshl_add_u64 v[16:17], s[58:59], 2, v[2:3]
	global_store_dword v[16:17], v13, off

; __device__ __forceinline__ float wave_sum(float v, int lane) {
; #pragma unroll
;     for (int o = 1; o < 64; o <<= 1) v += __uint_as_float((unsigned)__builtin_amdgcn_ds_bpermute((lane ^ o) << 2, (int)__float_as_uint(v)));
;     return v;
; }
; __device__ __forceinline__ void norm_row(const float* xrow, const float* g, bf16_t* orow, float* copy, int lane) {
;     const f32x4* xr = (const f32x4*)xrow + lane; f32x4 v[8]; float s = 0.f;
; #pragma unroll
;     for (int j = 0; j < 8; ++j) { v[j] = xr[64 * j]; s += (v[j].x * v[j].x + v[j].y * v[j].y) + (v[j].z * v[j].z + v[j].w * v[j].w); }
;     const float rs = rsqrtf(wave_sum(s, lane) * (1.f / DM) + EPS);
;     u32x2* o8 = (u32x2*)orow + lane; const f32x4* gr = (const f32x4*)g + lane;
.LBB0_190:
	global_load_dwordx4 v[24:27], v194, s[42:43]
	global_load_dwordx4 v[28:31], v194, s[42:43] offset:1024
	global_load_dwordx4 v[32:35], v194, s[42:43] offset:2048
	global_load_dwordx4 v[36:39], v194, s[42:43] offset:3072
	v_lshl_add_u64 v[0:1], s[42:43], 0, v[194:195]
	s_movk_i32 s29, 0x1000
	v_add_co_u32_e32 v48, vcc, s29, v0
	s_lshl_b64 s[40:41], s[40:41], 12
	s_nop 0
	v_addc_co_u32_e32 v49, vcc, 0, v1, vcc
	global_load_dwordx4 v[40:43], v[48:49], off
	global_load_dwordx4 v[44:47], v[48:49], off offset:1024
	global_load_dwordx4 v[0:3], v[48:49], off offset:3072
	s_nop 0
	global_load_dwordx4 v[48:51], v[48:49], off offset:2048
	s_nop 0
	global_load_dwordx4 v[52:55], v[6:7], off
	s_add_u32 s48, s48, s50
	s_addc_u32 s49, s49, s51
	s_add_u32 s36, s36, s38
	s_addc_u32 s37, s37, s39
	s_cmpk_lt_i32 s48, 0x800
	s_waitcnt vmcnt(0)
	v_mov_b32_e32 v58, v25
	s_waitcnt vmcnt(7)
	v_mov_b32_e32 v59, v29
	v_mov_b32_e32 v62, v27
	v_mov_b32_e32 v63, v31
	v_mov_b32_e32 v56, v24
	v_mov_b32_e32 v57, v28
	v_mov_b32_e32 v60, v26
	v_mov_b32_e32 v61, v30
	s_waitcnt vmcnt(6)
	v_pk_mul_f32 v[64:65], v[34:35], v[34:35]
	v_pk_mul_f32 v[66:67], v[32:33], v[32:33]
	v_pk_mul_f32 v[58:59], v[58:59], v[58:59]
	v_pk_mul_f32 v[62:63], v[62:63], v[62:63]
	v_pk_mov_b32 v[70:71], v[66:67], v[64:65] op_sel:[1,0]
	v_mov_b32_e32 v67, v65
	v_pk_fma_f32 v[56:57], v[56:57], v[56:57], v[58:59]
	v_pk_fma_f32 v[58:59], v[60:61], v[60:61], v[62:63]
	s_waitcnt vmcnt(5)
	v_mul_f32_e32 v8, v37, v37
	v_mul_f32_e32 v68, v39, v39
	v_pk_add_f32 v[60:61], v[70:71], v[66:67]
	v_pk_add_f32 v[56:57], v[56:57], v[58:59]
	v_pk_fma_f32 v[64:65], v[36:37], v[36:37], v[8:9] op_sel_hi:[1,1,0]
	v_pk_fma_f32 v[68:69], v[38:39], v[38:39], v[68:69] op_sel_hi:[1,1,0]
	s_waitcnt vmcnt(4)
	v_mul_f32_e32 v23, v40, v40
	v_mul_f32_e32 v72, v41, v41
	v_pk_add_f32 v[58:59], v[60:61], v[60:61] op_sel:[0,1] op_sel_hi:[1,0]
	v_pk_add_f32 v[56:57], v[56:57], v[56:57] op_sel:[0,1] op_sel_hi:[1,0]
	v_mul_f32_e32 v65, v42, v42
	v_mul_f32_e32 v69, v43, v43
	s_waitcnt vmcnt(3)
	v_pk_mul_f32 v[62:63], v[46:47], v[46:47]
	v_pk_mul_f32 v[66:67], v[44:45], v[44:45]
	v_mov_b32_e32 v59, v72
	v_mov_b32_e32 v57, v23
	v_pk_mov_b32 v[60:61], v[66:67], v[62:63] op_sel:[1,0]
	v_mov_b32_e32 v67, v63
	v_pk_add_f32 v[64:65], v[64:65], v[68:69]
	v_pk_add_f32 v[56:57], v[56:57], v[58:59]
	s_waitcnt vmcnt(1)
	v_mul_f32_e32 v8, v49, v49
	v_mul_f32_e32 v70, v51, v51
	v_pk_add_f32 v[60:61], v[60:61], v[66:67]
	v_pk_add_f32 v[56:57], v[56:57], v[64:65]
	v_mul_f32_e32 v73, v0, v0
	v_mul_f32_e32 v74, v1, v1
	v_mul_f32_e32 v75, v2, v2
	v_mul_f32_e32 v76, v3, v3
	v_pk_fma_f32 v[62:63], v[48:49], v[48:49], v[8:9] op_sel_hi:[1,1,0]
	v_pk_fma_f32 v[70:71], v[50:51], v[50:51], v[70:71] op_sel_hi:[1,1,0]
	v_pk_add_f32 v[60:61], v[60:61], v[60:61] op_sel:[0,1] op_sel_hi:[1,0]
	v_pk_add_f32 v[56:57], v[56:57], v[56:57] op_sel:[0,1] op_sel_hi:[1,0]
	v_mov_b32_e32 v63, v75
	v_mov_b32_e32 v71, v76
	v_mov_b32_e32 v61, v74
	v_mov_b32_e32 v57, v73
	v_pk_add_f32 v[62:63], v[62:63], v[70:71]
	v_pk_add_f32 v[56:57], v[56:57], v[60:61]
	s_nop 0
	v_pk_add_f32 v[56:57], v[56:57], v[62:63]
	s_nop 0
	v_add_f32_e32 v8, v56, v57
	s_nop 1
	v_mov_b32_dpp v23, v8 quad_perm:[1,0,3,2] row_mask:0xf bank_mask:0xf
	v_lshl_add_u64 v[56:57], v[4:5], 0, s[40:41]
	s_waitcnt lgkmcnt(0)
	v_add_f32_e32 v8, v8, v23
	s_nop 1
	v_mov_b32_dpp v23, v8 quad_perm:[2,3,0,1] row_mask:0xf bank_mask:0xf
	s_waitcnt lgkmcnt(0)
	v_add_f32_e32 v8, v8, v23
	s_nop 1
	v_mov_b32_dpp v23, v8 row_half_mirror row_mask:0xf bank_mask:0xf
	s_waitcnt lgkmcnt(0)
	v_add_f32_e32 v8, v8, v23
	s_nop 1
	v_mov_b32_dpp v23, v8 row_mirror row_mask:0xf bank_mask:0xf
	s_waitcnt lgkmcnt(0)
; __device__ __forceinline__ unsigned cvt_pk_bf16(float lo, float hi) { unsigned r; asm volatile("v_cvt_pk_bf16_f32 %0, %1, %2" : "=v"(r) : "v"(lo), "v"(hi)); return r; }
; __device__ __forceinline__ void norm_row(const float* xrow, const float* g, bf16_t* orow, float* copy, int lane) {
;     ...
;     const float rs = rsqrtf(wave_sum(s, lane) * (1.f / DM) + EPS);
;     u32x2* o8 = (u32x2*)orow + lane; const f32x4* gr = (const f32x4*)g + lane;
; #pragma unroll
;     for (int j = 0; j < 8; ++j) { const f32x4 gv = gr[64 * j]; u32x2 w; w.x = cvt_pk_bf16(v[j].x * rs * gv.x, v[j].y * rs * gv.y); w.y = cvt_pk_bf16(v[j].z * rs * gv.z, v[j].w * rs * gv.w); o8[64 * j] = w; }
	v_add_f32_e32 v8, v8, v23
	ds_bpermute_b32 v23, v21, v8
	s_waitcnt lgkmcnt(0)
	v_add_f32_e32 v8, v8, v23
	ds_bpermute_b32 v23, v22, v8
	s_waitcnt lgkmcnt(0)
	v_add_f32_e32 v8, v8, v23
	v_fmamk_f32 v8, v8, 0x3a000000, v196
	v_mul_f32_e32 v23, 0x4b800000, v8
	v_cmp_gt_f32_e32 vcc, s78, v8
	s_nop 1
	v_cndmask_b32_e32 v8, v8, v23, vcc
	v_rsq_f32_e32 v8, v8
	s_nop 0
	v_mul_f32_e32 v23, 0x45800000, v8
	v_cndmask_b32_e32 v8, v8, v23, vcc
	v_mul_f32_e32 v23, v24, v8
	v_mul_f32_e32 v24, v25, v8
	v_mul_f32_e32 v25, v26, v8
	v_mul_f32_e32 v26, v27, v8
	s_waitcnt vmcnt(0)
	v_mul_f32_e32 v24, v53, v24
	v_mul_f32_e32 v25, v54, v25
	v_mul_f32_e32 v23, v52, v23
	v_mul_f32_e32 v26, v55, v26
	v_cvt_pk_bf16_f32 v24, v23, v24
	v_cvt_pk_bf16_f32 v25, v25, v26
	global_store_dwordx2 v[56:57], v[24:25], off
	global_load_dwordx4 v[24:27], v[6:7], off offset:1024
	v_mul_f32_e32 v23, v28, v8
	v_mul_f32_e32 v28, v29, v8
	v_mul_f32_e32 v29, v30, v8
	v_mul_f32_e32 v30, v31, v8
	v_mul_f32_e32 v0, v0, v8
	v_mul_f32_e32 v1, v1, v8
	v_mul_f32_e32 v2, v2, v8
	v_mul_f32_e32 v3, v3, v8
	s_waitcnt vmcnt(0)
	v_mul_f32_e32 v23, v24, v23
	v_mul_f32_e32 v24, v25, v28
	v_mul_f32_e32 v25, v26, v29
	v_mul_f32_e32 v26, v27, v30
	v_cvt_pk_bf16_f32 v24, v23, v24
	v_cvt_pk_bf16_f32 v25, v25, v26
	global_store_dwordx2 v[56:57], v[24:25], off offset:512
	global_load_dwordx4 v[24:27], v[6:7], off offset:2048
	v_mul_f32_e32 v23, v32, v8
	v_mul_f32_e32 v28, v33, v8
	v_mul_f32_e32 v29, v34, v8
	v_mul_f32_e32 v30, v35, v8
	s_waitcnt vmcnt(0)
	v_mul_f32_e32 v23, v24, v23
	v_mul_f32_e32 v24, v25, v28
	v_mul_f32_e32 v25, v26, v29
	v_mul_f32_e32 v26, v27, v30
	v_cvt_pk_bf16_f32 v24, v23, v24
	v_cvt_pk_bf16_f32 v25, v25, v26
	global_store_dwordx2 v[56:57], v[24:25], off offset:1024
	global_load_dwordx4 v[24:27], v[6:7], off offset:3072
	v_mul_f32_e32 v23, v36, v8
	v_mul_f32_e32 v28, v37, v8
	v_mul_f32_e32 v29, v38, v8
	v_mul_f32_e32 v30, v39, v8
	s_waitcnt vmcnt(0)
	v_mul_f32_e32 v23, v23, v24
	v_mul_f32_e32 v24, v28, v25
	v_mul_f32_e32 v25, v29, v26
	v_mul_f32_e32 v26, v30, v27
	v_cvt_pk_bf16_f32 v24, v23, v24
	v_cvt_pk_bf16_f32 v25, v25, v26
	global_store_dwordx2 v[56:57], v[24:25], off offset:1536
	global_load_dwordx4 v[24:27], v[10:11], off
	v_mul_f32_e32 v23, v40, v8
	v_mul_f32_e32 v28, v41, v8
	v_mul_f32_e32 v29, v42, v8
	v_mul_f32_e32 v30, v43, v8
	s_waitcnt vmcnt(0)
	v_mul_f32_e32 v23, v23, v24
	v_mul_f32_e32 v24, v28, v25
	v_mul_f32_e32 v25, v29, v26
	v_mul_f32_e32 v26, v30, v27
	v_cvt_pk_bf16_f32 v24, v23, v24
	v_cvt_pk_bf16_f32 v25, v25, v26
	global_store_dwordx2 v[56:57], v[24:25], off offset:2048
	global_load_dwordx4 v[24:27], v[12:13], off
	v_mul_f32_e32 v23, v44, v8
	v_mul_f32_e32 v28, v45, v8
	v_mul_f32_e32 v29, v46, v8
	v_mul_f32_e32 v30, v47, v8
	s_waitcnt vmcnt(0)
	v_mul_f32_e32 v23, v23, v24
	v_mul_f32_e32 v24, v28, v25
	v_mul_f32_e32 v25, v29, v26
	v_mul_f32_e32 v26, v30, v27
	v_cvt_pk_bf16_f32 v24, v23, v24
	v_cvt_pk_bf16_f32 v25, v25, v26
	global_store_dwordx2 v[56:57], v[24:25], off offset:2560
	global_load_dwordx4 v[24:27], v[14:15], off
	v_mul_f32_e32 v23, v48, v8
	v_mul_f32_e32 v28, v49, v8
	v_mul_f32_e32 v29, v50, v8
	v_mul_f32_e32 v30, v51, v8
	s_waitcnt vmcnt(0)
	v_mul_f32_e32 v23, v23, v24
	v_mul_f32_e32 v24, v28, v25
	v_mul_f32_e32 v25, v29, v26
	v_mul_f32_e32 v26, v30, v27
	v_cvt_pk_bf16_f32 v24, v23, v24
	v_cvt_pk_bf16_f32 v25, v25, v26
	global_store_dwordx2 v[56:57], v[24:25], off offset:3072
	global_load_dwordx4 v[24:27], v[16:17], off
	s_waitcnt vmcnt(0)
	v_mul_f32_e32 v0, v0, v24
	v_mul_f32_e32 v1, v1, v25
	v_mul_f32_e32 v2, v2, v26
	v_mul_f32_e32 v3, v3, v27
	v_cvt_pk_bf16_f32 v0, v0, v1
	v_cvt_pk_bf16_f32 v1, v2, v3
	global_store_dwordx2 v[56:57], v[0:1], off offset:3584
	s_cbranch_scc0 .LBB0_195

; __device__ __forceinline__ unsigned cvt_pk_bf16(float lo, float hi) { unsigned r; asm volatile("v_cvt_pk_bf16_f32 %0, %1, %2" : "=v"(r) : "v"(lo), "v"(hi)); return r; }
; __device__ __forceinline__ float bf2f(unsigned short h) { return __uint_as_float(((unsigned)h) << 16); }
; __device__ __forceinline__ float bflo(unsigned w) { return __uint_as_float(w << 16); }
; __device__ __forceinline__ float bfhi(unsigned w) { return __uint_as_float(w & 0xffff0000u); }
; __global__ void __launch_bounds__(512) mega_fwd(Params P) {
;     ...
;             for (int part = 0; part < 2; ++part) { const u32x4 w = part ? wk : wq; float v[8] = {bflo(w.x), bfhi(w.x), bflo(w.y), bfhi(w.y), bflo(w.z), bfhi(w.z), bflo(w.w), bfhi(w.w)};
;                 float ss = 0.f;
; #pragma unroll
;                 for (int e = 0; e < 8; ++e) ss += v[e] * v[e];
;                 const float rs = rsqrtf(wave_sum(ss, lane) * (1.f / 512.f) + EPS); const float* gg = (part ? g_kv : g_q) + lane * 8; const f32x4 g0 = *(const f32x4*)gg, g1 = *(const f32x4*)(gg + 4);
;                 u32x4 o; o.x = cvt_pk_bf16(v[0] * rs * g0.x, v[1] * rs * g0.y); o.y = cvt_pk_bf16(v[2] * rs * g0.z, v[3] * rs * g0.w); o.z = cvt_pk_bf16(v[4] * rs * g1.x, v[5] * rs * g1.y); o.w = cvt_pk_bf16(v[6] * rs * g1.z, v[7] * rs * g1.w);
;                 *(u32x4*)((part ? CKVN : CQN) + (size_t)m * 512 + lane * 8) = o; }
;             { const float x1 = bf2f(kx1), x2 = bf2f(kx2); const float o1 = x1 * cs.x - x2 * cs.y, o2 = x2 * cs.x + x1 * cs.y;
;               bf16_t* kr2 = KR2 + (size_t)m * 64; if (lane < 32) { kr2[lane] = (bf16_t)(cvt_pk_bf16(o1, o1) & 0xffff); kr2[32 + lane] = (bf16_t)(cvt_pk_bf16(o2, o2) & 0xffff); } }
.LBB0_503:
	s_waitcnt vmcnt(4)
	v_and_b32_e32 v56, 0xffff0000, v20
	v_lshlrev_b32_e32 v49, 16, v20
	v_mul_f32_e32 v50, v56, v56
	v_lshlrev_b32_e32 v57, 16, v21
	v_fmac_f32_e32 v50, v49, v49
	v_and_b32_e32 v58, 0xffff0000, v21
	v_fmac_f32_e32 v50, v57, v57
	v_lshlrev_b32_e32 v36, 16, v22
	v_and_b32_e32 v37, 0xffff0000, v22
	v_fmac_f32_e32 v50, v58, v58
	v_pk_mul_f32 v[20:21], v[36:37], v[36:37]
	v_lshlrev_b32_e32 v54, 16, v23
	v_add_f32_e32 v20, v50, v20
	v_and_b32_e32 v55, 0xffff0000, v23
	v_add_f32_e32 v22, v20, v21
	v_pk_mul_f32 v[20:21], v[54:55], v[54:55]
	s_mov_b32 s38, 0x28400000
	v_add_f32_e32 v20, v22, v20
	v_add_f32_e32 v20, v20, v21
	s_nop 1
	v_mov_b32_dpp v21, v20 quad_perm:[1,0,3,2] row_mask:0xf bank_mask:0xf
	s_waitcnt lgkmcnt(0)
	v_add_f32_e32 v20, v20, v21
	s_nop 1
	v_mov_b32_dpp v21, v20 quad_perm:[2,3,0,1] row_mask:0xf bank_mask:0xf
	s_waitcnt lgkmcnt(0)
	v_add_f32_e32 v20, v20, v21
	s_nop 1
	v_mov_b32_dpp v21, v20 row_half_mirror row_mask:0xf bank_mask:0xf
	s_waitcnt lgkmcnt(0)
	v_add_f32_e32 v20, v20, v21
	s_nop 1
	v_mov_b32_dpp v21, v20 row_mirror row_mask:0xf bank_mask:0xf
	s_waitcnt lgkmcnt(0)
	v_add_f32_e32 v20, v20, v21
	ds_bpermute_b32 v21, v45, v20
	s_waitcnt lgkmcnt(0)
	v_add_f32_e32 v20, v20, v21
	ds_bpermute_b32 v21, v46, v20
	s_waitcnt lgkmcnt(0)
	v_add_f32_e32 v20, v20, v21
	v_fmamk_f32 v20, v20, 0x3b000000, v196
	v_cmp_gt_f32_e32 vcc, s78, v20
	v_mul_f32_e32 v21, 0x4b800000, v20
	s_nop 0
	v_cndmask_b32_e32 v20, v20, v21, vcc
	v_rsq_f32_e32 v20, v20
	s_nop 0
	v_mul_f32_e32 v21, 0x45800000, v20
	v_cndmask_b32_e32 v59, v20, v21, vcc
	global_load_dwordx4 v[50:53], v[24:25], off offset:16
	global_load_dwordx4 v[20:23], v[24:25], off
	v_mul_f32_e32 v49, v59, v49
	s_waitcnt vmcnt(0)
	v_mul_f32_e32 v20, v49, v20
	v_mul_f32_e32 v49, v59, v56
	v_mul_f32_e32 v21, v49, v21
	v_cvt_pk_bf16_f32 v20, v20, v21
	v_mul_f32_e32 v21, v59, v57
	v_mul_f32_e32 v21, v21, v22
	v_mul_f32_e32 v22, v59, v58
	v_mul_f32_e32 v22, v22, v23
	v_cvt_pk_bf16_f32 v21, v21, v22
	v_mul_f32_e32 v22, v59, v36
	v_mul_f32_e32 v23, v59, v37
	v_mul_f32_e32 v22, v22, v50
	v_mul_f32_e32 v23, v23, v51
	v_cvt_pk_bf16_f32 v22, v22, v23
	v_mul_f32_e32 v23, v59, v54
	v_mul_f32_e32 v36, v59, v55
	v_mul_f32_e32 v23, v23, v52
	v_mul_f32_e32 v36, v36, v53
	v_cvt_pk_bf16_f32 v23, v23, v36
	v_lshl_add_u64 v[36:37], s[48:49], 0, v[28:29]
	v_add_co_u32_e32 v50, vcc, s38, v36
	v_and_b32_e32 v56, 0xffff0000, v16
	s_nop 0
	v_addc_co_u32_e32 v51, vcc, 0, v37, vcc
	global_store_dwordx4 v[50:51], v[20:23], off
	s_load_dwordx2 s[38:39], s[46:47], 0x60
	v_lshlrev_b32_e32 v49, 16, v16
	v_mul_f32_e32 v20, v56, v56
	v_lshlrev_b32_e32 v57, 16, v17
	v_fmac_f32_e32 v20, v49, v49
	v_and_b32_e32 v58, 0xffff0000, v17
	v_fmac_f32_e32 v20, v57, v57
	v_lshlrev_b32_e32 v22, 16, v18
	v_and_b32_e32 v23, 0xffff0000, v18
	v_fmac_f32_e32 v20, v58, v58
	v_pk_mul_f32 v[16:17], v[22:23], v[22:23]
	v_lshlrev_b32_e32 v54, 16, v19
	v_add_f32_e32 v16, v20, v16
	v_and_b32_e32 v55, 0xffff0000, v19
	s_waitcnt lgkmcnt(0)
	s_add_u32 s38, s38, s58
	v_add_f32_e32 v18, v16, v17
	v_pk_mul_f32 v[16:17], v[54:55], v[54:55]
	s_addc_u32 s39, s39, s59
	v_add_f32_e32 v16, v18, v16
	global_load_dwordx4 v[18:21], v194, s[38:39] offset:16
	global_load_dwordx4 v[50:53], v194, s[38:39]
	v_add_f32_e32 v16, v16, v17
	s_nop 1
	v_mov_b32_dpp v17, v16 quad_perm:[1,0,3,2] row_mask:0xf bank_mask:0xf
	s_waitcnt lgkmcnt(0)
	v_add_f32_e32 v16, v16, v17
	s_nop 1
	v_mov_b32_dpp v17, v16 quad_perm:[2,3,0,1] row_mask:0xf bank_mask:0xf
	s_waitcnt lgkmcnt(0)
	v_add_f32_e32 v16, v16, v17
	s_nop 1
	v_mov_b32_dpp v17, v16 row_half_mirror row_mask:0xf bank_mask:0xf
	s_waitcnt lgkmcnt(0)
	v_add_f32_e32 v16, v16, v17
	s_nop 1
	v_mov_b32_dpp v17, v16 row_mirror row_mask:0xf bank_mask:0xf
	s_waitcnt lgkmcnt(0)
	v_add_f32_e32 v16, v16, v17
	ds_bpermute_b32 v17, v45, v16
	s_waitcnt lgkmcnt(0)
	v_add_f32_e32 v16, v16, v17
	ds_bpermute_b32 v17, v46, v16
	s_waitcnt lgkmcnt(0)
	v_add_f32_e32 v16, v16, v17
	v_fmamk_f32 v16, v16, 0x3b000000, v196
	v_cmp_gt_f32_e32 vcc, s78, v16
	v_mul_f32_e32 v17, 0x4b800000, v16
	s_nop 0
	v_cndmask_b32_e32 v16, v16, v17, vcc
	v_rsq_f32_e32 v16, v16
	s_nop 0
	v_mul_f32_e32 v17, 0x45800000, v16
	v_cndmask_b32_e32 v59, v16, v17, vcc
	v_mul_f32_e32 v16, v59, v49
	v_mul_f32_e32 v17, v59, v56
	v_mul_f32_e32 v22, v59, v22
	v_mul_f32_e32 v49, v59, v58
	s_waitcnt vmcnt(1)
	v_mul_f32_e32 v18, v22, v18
	s_waitcnt vmcnt(0)
	v_mul_f32_e32 v16, v16, v50
	v_mul_f32_e32 v17, v17, v51
	v_cvt_pk_bf16_f32 v16, v16, v17
	v_mul_f32_e32 v17, v59, v57
	v_mul_f32_e32 v22, v59, v23
	v_mul_f32_e32 v17, v17, v52
	v_mul_f32_e32 v19, v22, v19
	v_mul_f32_e32 v49, v49, v53
	v_cvt_pk_bf16_f32 v17, v17, v49
	v_cvt_pk_bf16_f32 v18, v18, v19
	v_mul_f32_e32 v19, v59, v54
	v_mul_f32_e32 v19, v19, v20
	v_mul_f32_e32 v20, v59, v55
	v_mul_f32_e32 v20, v20, v21
	v_cvt_pk_bf16_f32 v19, v19, v20
	v_add_co_u32_e32 v20, vcc, 0x2ac00000, v36
	s_nop 1
	v_addc_co_u32_e32 v21, vcc, 0, v37, vcc
	global_store_dwordx4 v[20:21], v[16:19], off
	s_and_saveexec_b64 s[64:65], s[42:43]
	s_cbranch_execz .LBB0_494
	v_lshlrev_b32_e32 v16, 16, v48
	v_lshlrev_b32_e32 v17, 16, v47
	v_mul_f32_e32 v18, v38, v16
	v_mul_f32_e32 v16, v39, v16
	v_fma_f32 v16, v38, v17, -v16
	v_fmac_f32_e32 v18, v39, v17
	v_cvt_pk_bf16_f32 v19, v16, v16
	v_lshl_add_u64 v[16:17], s[48:49], 0, v[30:31]
	v_add_co_u32_e32 v16, vcc, 0x3f200000, v16
	s_nop 1
	v_addc_co_u32_e32 v17, vcc, 0, v17, vcc
	global_store_short v[16:17], v19, off
	v_cvt_pk_bf16_f32 v18, v18, v18
	global_store_short v[16:17], v18, off offset:64
	s_branch .LBB0_494

; __device__ __forceinline__ float bflo(unsigned w) { return __uint_as_float(w << 16); }
; __device__ __forceinline__ float bfhi(unsigned w) { return __uint_as_float(w & 0xffff0000u); }
; __global__ void __launch_bounds__(512) mega_fwd(Params P) {
;     ...
;         for (int m = gw; m < MTOK; m += NGW) {
;             bf16_t* yn = XN + (size_t)m * 2048;
;             const u32x4 wa = *(const u32x4*)(YA + (size_t)m * 768 + lane * 8), wb = *(const u32x4*)(YB + (size_t)m * 768 + lane * 8), wc_ = *(const u32x4*)(YC + (size_t)m * 512 + lane * 8);
;             const u32x2 wa2 = *(const u32x2*)(YA + (size_t)m * 768 + 512 + lane * 4), wb2 = *(const u32x2*)(YB + (size_t)m * 768 + 512 + lane * 4);
; #pragma unroll
;             for (int part = 0; part < 2; ++part) { const float* gg = part ? g_ob : g_oa;
;                 const u32x4 w = part ? wb : wa; const u32x2 w2 = part ? wb2 : wa2;
;                 float v[12] = {bflo(w.x), bfhi(w.x), bflo(w.y), bfhi(w.y), bflo(w.z), bfhi(w.z), bflo(w.w), bfhi(w.w), bflo(w2.x), bfhi(w2.x), bflo(w2.y), bfhi(w2.y)};
;                 float ss = 0.f;
; #pragma unroll
;                 for (int e = 0; e < 12; ++e) ss += v[e] * v[e];
;                 const float rs = rsqrtf(wave_sum(ss, lane) * (1.f / 768.f) + EPS); const f32x4 g0 = *(const f32x4*)(gg + lane * 8), g1 = *(const f32x4*)(gg + lane * 8 + 4), g2 = *(const f32x4*)(gg + 512 + lane * 4);
.LBB0_1365:
	v_lshl_add_u64 v[30:31], s[52:53], 0, v[16:17]
	v_lshl_add_u64 v[44:45], s[52:53], 0, v[20:21]
	v_lshl_add_u64 v[28:29], s[52:53], 0, v[24:25]
	global_load_dwordx4 v[4:7], v[12:13], off offset:16
	global_load_dwordx4 v[8:11], v[12:13], off
	global_load_dwordx4 v[0:3], v[14:15], off offset:2048
	global_load_dwordx4 v[40:43], v[30:31], off
	v_add_co_u32_e64 v30, s[42:43], s90, v44
	v_lshl_add_u64 v[46:47], s[52:53], 0, v[18:19]
	v_add_co_u32_e32 v48, vcc, 0x1df00000, v28
	v_addc_co_u32_e64 v31, s[42:43], 0, v45, s[42:43]
	v_add_co_u32_e64 v52, s[42:43], s90, v46
	v_addc_co_u32_e32 v49, vcc, 0, v29, vcc
	s_nop 0
	v_addc_co_u32_e64 v53, s[42:43], 0, v47, s[42:43]
	global_load_dwordx4 v[44:47], v[48:49], off
	v_add_co_u32_e32 v28, vcc, 0x28400000, v28
	v_lshl_add_u64 v[26:27], s[52:53], 0, v[22:23]
	s_nop 0
	v_addc_co_u32_e32 v29, vcc, 0, v29, vcc
	s_mov_b32 s38, 0x1df00000
	v_add_co_u32_e32 v54, vcc, s38, v26
	global_load_dwordx4 v[48:51], v[28:29], off
	s_nop 0
	v_addc_co_u32_e32 v55, vcc, 0, v27, vcc
	v_add_co_u32_e32 v26, vcc, 0x28400000, v26
	v_lshl_add_u64 v[16:17], v[16:17], 0, s[54:55]
	s_nop 0
	v_addc_co_u32_e32 v27, vcc, 0, v27, vcc
	global_load_dwordx2 v[26:27], v[26:27], off offset:1024
	v_lshl_add_u64 v[18:19], v[18:19], 0, s[56:57]
	global_load_dwordx2 v[28:29], v[54:55], off offset:1024
	v_lshl_add_u64 v[20:21], v[20:21], 0, s[56:57]
	v_lshl_add_u64 v[22:23], v[22:23], 0, s[58:59]
	v_lshl_add_u64 v[24:25], v[24:25], 0, s[58:59]
	s_waitcnt vmcnt(4)
	v_lshlrev_b32_e32 v60, 16, v41
	v_and_b32_e32 v61, 0xffff0000, v41
	v_and_b32_e32 v59, 0xffff0000, v40
	v_lshlrev_b32_e32 v58, 16, v40
	v_lshlrev_b32_e32 v40, 16, v42
	s_waitcnt vmcnt(3)
	v_and_b32_e32 v62, 0xffff0000, v44
	v_lshlrev_b32_e32 v41, 16, v44
	v_mul_f32_e32 v69, v62, v62
	v_lshlrev_b32_e32 v63, 16, v45
	v_fmac_f32_e32 v69, v41, v41
	v_and_b32_e32 v64, 0xffff0000, v45
	v_fmac_f32_e32 v69, v63, v63
	v_lshlrev_b32_e32 v65, 16, v46
	v_fmac_f32_e32 v69, v64, v64
	v_and_b32_e32 v66, 0xffff0000, v46
	v_fmac_f32_e32 v69, v65, v65
	v_lshlrev_b32_e32 v67, 16, v47
	v_fmac_f32_e32 v69, v66, v66
	v_and_b32_e32 v68, 0xffff0000, v47
	v_fmac_f32_e32 v69, v67, v67
	v_fmac_f32_e32 v69, v68, v68
	s_waitcnt vmcnt(2)
	v_lshlrev_b32_e32 v70, 16, v48
	v_and_b32_e32 v71, 0xffff0000, v48
	v_lshlrev_b32_e32 v72, 16, v49
	s_waitcnt vmcnt(0)
	v_lshlrev_b32_e32 v44, 16, v28
	v_and_b32_e32 v45, 0xffff0000, v28
	v_pk_mul_f32 v[46:47], v[44:45], v[44:45]
	v_lshlrev_b32_e32 v28, 16, v29
	v_and_b32_e32 v29, 0xffff0000, v29
	v_add_f32_e32 v46, v69, v46
	v_and_b32_e32 v73, 0xffff0000, v49
	v_pk_mul_f32 v[48:49], v[28:29], v[28:29]
	v_add_f32_e32 v46, v46, v47
	v_add_f32_e32 v46, v46, v48
	v_add_f32_e32 v46, v46, v49
	s_nop 1
	v_mov_b32_dpp v48, v46 quad_perm:[1,0,3,2] row_mask:0xf bank_mask:0xf
	v_mul_f32_e32 v78, v71, v71
	v_fmac_f32_e32 v78, v70, v70
	v_fmac_f32_e32 v78, v72, v72
	v_lshlrev_b32_e32 v74, 16, v50
	s_waitcnt lgkmcnt(0)
	v_add_f32_e32 v46, v46, v48
	s_nop 1
	v_mov_b32_dpp v48, v46 quad_perm:[2,3,0,1] row_mask:0xf bank_mask:0xf
	v_fmac_f32_e32 v78, v73, v73
	v_and_b32_e32 v75, 0xffff0000, v50
	v_fmac_f32_e32 v78, v74, v74
	v_lshlrev_b32_e32 v76, 16, v51
	s_waitcnt lgkmcnt(0)
	v_add_f32_e32 v46, v46, v48
	s_nop 1
	v_mov_b32_dpp v48, v46 row_half_mirror row_mask:0xf bank_mask:0xf
	v_fmac_f32_e32 v78, v75, v75
	v_and_b32_e32 v77, 0xffff0000, v51
	v_lshlrev_b32_e32 v50, 16, v26
	v_and_b32_e32 v51, 0xffff0000, v26
	s_waitcnt lgkmcnt(0)
	v_add_f32_e32 v46, v46, v48
	s_nop 1
	v_mov_b32_dpp v48, v46 row_mirror row_mask:0xf bank_mask:0xf
	v_fmac_f32_e32 v78, v76, v76
	v_pk_mul_f32 v[54:55], v[50:51], v[50:51]
	v_fmac_f32_e32 v78, v77, v77
	v_lshlrev_b32_e32 v26, 16, v27
	s_waitcnt lgkmcnt(0)
	v_add_f32_e32 v46, v46, v48
	ds_bpermute_b32 v48, v36, v46
	v_and_b32_e32 v27, 0xffff0000, v27
	v_add_f32_e32 v47, v78, v54
	v_pk_mul_f32 v[56:57], v[26:27], v[26:27]
	v_add_f32_e32 v47, v47, v55
	s_waitcnt lgkmcnt(0)
	v_add_f32_e32 v46, v46, v48
	ds_bpermute_b32 v48, v37, v46
	v_add_f32_e32 v47, v47, v56
	v_add_f32_e32 v47, v47, v57
	s_nop 1
	v_mov_b32_dpp v49, v47 quad_perm:[1,0,3,2] row_mask:0xf bank_mask:0xf
	s_waitcnt lgkmcnt(0)
	v_add_f32_e32 v46, v46, v48
	v_fmamk_f32 v46, v46, 0x3aaaaaab, v196
	v_mul_f32_e32 v48, 0x4b800000, v46
	v_cmp_gt_f32_e32 vcc, s78, v46
	s_waitcnt lgkmcnt(0)
; __device__ __forceinline__ unsigned cvt_pk_bf16(float lo, float hi) { unsigned r; asm volatile("v_cvt_pk_bf16_f32 %0, %1, %2" : "=v"(r) : "v"(lo), "v"(hi)); return r; }
; __global__ void __launch_bounds__(512) mega_fwd(Params P) {
;     ...
;             for (int part = 0; part < 2; ++part) { const float* gg = part ? g_ob : g_oa;
;                 const u32x4 w = part ? wb : wa; const u32x2 w2 = part ? wb2 : wa2;
;                 float v[12] = {bflo(w.x), bfhi(w.x), bflo(w.y), bfhi(w.y), bflo(w.z), bfhi(w.z), bflo(w.w), bfhi(w.w), bflo(w2.x), bfhi(w2.x), bflo(w2.y), bfhi(w2.y)};
;                 float ss = 0.f;
; #pragma unroll
;                 for (int e = 0; e < 12; ++e) ss += v[e] * v[e];
;                 const float rs = rsqrtf(wave_sum(ss, lane) * (1.f / 768.f) + EPS); const f32x4 g0 = *(const f32x4*)(gg + lane * 8), g1 = *(const f32x4*)(gg + lane * 8 + 4), g2 = *(const f32x4*)(gg + 512 + lane * 4);
;                 u32x4 o; o.x = cvt_pk_bf16(v[0] * rs * g0.x, v[1] * rs * g0.y); o.y = cvt_pk_bf16(v[2] * rs * g0.z, v[3] * rs * g0.w); o.z = cvt_pk_bf16(v[4] * rs * g1.x, v[5] * rs * g1.y); o.w = cvt_pk_bf16(v[6] * rs * g1.z, v[7] * rs * g1.w);
;                 u32x2 o2; o2.x = cvt_pk_bf16(v[8] * rs * g2.x, v[9] * rs * g2.y); o2.y = cvt_pk_bf16(v[10] * rs * g2.z, v[11] * rs * g2.w);
;     ...
;                 if (part == 0) { o = (u32x4){0u,0u,0u,0u}; o2 = (u32x2){0u,0u}; }
;     ...
;                 if (part == 1) { o = (u32x4){0u,0u,0u,0u}; o2 = (u32x2){0u,0u}; }
;     ...
;                 *(u32x4*)(yn + part * 768 + lane * 8) = o; *(u32x2*)(yn + part * 768 + 512 + lane * 4) = o2; }
;             { const u32x4 w = wc_; float v[8] = {bflo(w.x), bfhi(w.x), bflo(w.y), bfhi(w.y), bflo(w.z), bfhi(w.z), bflo(w.w), bfhi(w.w)};
;               float ss = 0.f;
; #pragma unroll
;               for (int e = 0; e < 8; ++e) ss += v[e] * v[e];
;               const float rs = rsqrtf(wave_sum(ss, lane) * (1.f / 512.f) + EPS); const f32x4 g0 = *(const f32x4*)(g_oc + lane * 8), g1 = *(const f32x4*)(g_oc + lane * 8 + 4);
;               u32x4 o; o.x = cvt_pk_bf16(v[0] * rs * g0.x, v[1] * rs * g0.y); o.y = cvt_pk_bf16(v[2] * rs * g0.z, v[3] * rs * g0.w); o.z = cvt_pk_bf16(v[4] * rs * g1.x, v[5] * rs * g1.y); o.w = cvt_pk_bf16(v[6] * rs * g1.z, v[7] * rs * g1.w);
;     ...
;               o = (u32x4){0u,0u,0u,0u};
;     ...
;               *(u32x4*)(yn + 1536 + lane * 8) = o; }
	v_add_f32_e32 v47, v47, v49
	v_cndmask_b32_e32 v46, v46, v48, vcc
	v_rsq_f32_e32 v46, v46
	s_nop 0
	v_mul_f32_e32 v48, 0x45800000, v46
	v_cndmask_b32_e32 v46, v46, v48, vcc
	v_mul_f32_e32 v41, v46, v41
	v_mul_f32_e32 v48, v46, v62
	v_mul_f32_e32 v49, v46, v63
	v_mul_f32_e32 v54, v46, v64
	v_mul_f32_e32 v55, v46, v65
	v_mul_f32_e32 v56, v46, v66
	v_mul_f32_e32 v57, v46, v67
	v_mul_f32_e32 v62, v46, v68
	v_mul_f32_e32 v44, v46, v44
	v_mul_f32_e32 v45, v46, v45
	v_mul_f32_e32 v28, v46, v28
	v_mul_f32_e32 v29, v46, v29
	v_mul_f32_e32 v8, v8, v41
	v_mul_f32_e32 v9, v9, v48
	v_mul_f32_e32 v10, v10, v49
	v_mul_f32_e32 v11, v11, v54
	v_mul_f32_e32 v4, v4, v55
	v_mul_f32_e32 v5, v5, v56
	v_mul_f32_e32 v6, v6, v57
	v_mul_f32_e32 v7, v7, v62
	v_mul_f32_e32 v41, v0, v44
	v_mul_f32_e32 v44, v1, v45
	v_mul_f32_e32 v28, v2, v28
	v_mul_f32_e32 v29, v3, v29
	v_cvt_pk_bf16_f32 v0, v8, v9
	v_cvt_pk_bf16_f32 v1, v10, v11
	v_cvt_pk_bf16_f32 v2, v4, v5
	v_cvt_pk_bf16_f32 v3, v6, v7
	v_cvt_pk_bf16_f32 v4, v41, v44
	v_cvt_pk_bf16_f32 v5, v28, v29
	global_store_dwordx4 v[30:31], v[0:3], off
	global_store_dwordx2 v[52:53], v[4:5], off offset:1024
	s_load_dwordx4 s[40:43], s[46:47], 0xb0
	s_nop 1
	v_mov_b32_dpp v28, v47 quad_perm:[2,3,0,1] row_mask:0xf bank_mask:0xf
	s_waitcnt lgkmcnt(0)
	s_add_u32 s38, s40, s28
	s_addc_u32 s39, s41, s29
	global_load_dwordx4 v[0:3], v38, s[38:39]
	global_load_dwordx4 v[4:7], v38, s[38:39] offset:16
	global_load_dwordx4 v[8:11], v39, s[38:39] offset:2048
	v_add_f32_e32 v28, v47, v28
	s_nop 1
	v_mov_b32_dpp v29, v28 row_half_mirror row_mask:0xf bank_mask:0xf
	s_add_u32 s38, s42, s60
	s_addc_u32 s39, s43, s61
	s_add_i32 s48, s48, s50
	s_cmp_lt_i32 s48, 0xa000
	s_waitcnt lgkmcnt(0)
	v_add_f32_e32 v28, v28, v29
	s_nop 1
	v_mov_b32_dpp v29, v28 row_mirror row_mask:0xf bank_mask:0xf
	s_waitcnt lgkmcnt(0)
	v_add_f32_e32 v28, v28, v29
	ds_bpermute_b32 v29, v36, v28
	s_waitcnt lgkmcnt(0)
	v_add_f32_e32 v28, v28, v29
	ds_bpermute_b32 v29, v37, v28
	s_waitcnt lgkmcnt(0)
	v_add_f32_e32 v28, v28, v29
	v_fmamk_f32 v28, v28, 0x3aaaaaab, v196
	v_mul_f32_e32 v29, 0x4b800000, v28
	v_cmp_gt_f32_e32 vcc, s78, v28
	s_nop 1
	v_cndmask_b32_e32 v28, v28, v29, vcc
	v_rsq_f32_e32 v28, v28
	s_nop 0
	v_mul_f32_e32 v29, 0x45800000, v28
	v_cndmask_b32_e32 v28, v28, v29, vcc
	v_mul_f32_e32 v29, v28, v70
	v_mul_f32_e32 v41, v28, v71
	v_mul_f32_e32 v44, v28, v72
	v_mul_f32_e32 v45, v28, v73
	v_mul_f32_e32 v46, v28, v74
	v_mul_f32_e32 v47, v28, v75
	v_mul_f32_e32 v48, v28, v76
	v_mul_f32_e32 v49, v28, v77
	v_mul_f32_e32 v50, v28, v50
	v_mul_f32_e32 v51, v28, v51
	v_mul_f32_e32 v26, v28, v26
	v_mul_f32_e32 v27, v28, v27
	v_mul_f32_e32 v28, v59, v59
	v_fmac_f32_e32 v28, v58, v58
	v_fmac_f32_e32 v28, v60, v60
	v_fmac_f32_e32 v28, v61, v61
	s_waitcnt vmcnt(2)
	v_mul_f32_e32 v0, v0, v29
	v_mul_f32_e32 v1, v1, v41
	v_mul_f32_e32 v2, v2, v44
	v_mul_f32_e32 v3, v3, v45
	s_waitcnt vmcnt(1)
	v_mul_f32_e32 v4, v4, v46
	v_mul_f32_e32 v5, v5, v47
	v_mul_f32_e32 v6, v6, v48
	v_mul_f32_e32 v7, v7, v49
	v_cvt_pk_bf16_f32 v0, v0, v1
	v_cvt_pk_bf16_f32 v1, v2, v3
	v_cvt_pk_bf16_f32 v2, v4, v5
	v_cvt_pk_bf16_f32 v3, v6, v7
	s_waitcnt vmcnt(0)
	v_mul_f32_e32 v8, v8, v50
	v_mul_f32_e32 v9, v9, v51
	v_mul_f32_e32 v10, v10, v26
	v_mul_f32_e32 v11, v11, v27
	v_cvt_pk_bf16_f32 v4, v8, v9
	v_cvt_pk_bf16_f32 v5, v10, v11
	global_store_dwordx4 v[30:31], v[0:3], off offset:1536
	global_store_dwordx2 v[52:53], v[4:5], off offset:2560
	global_load_dwordx4 v[0:3], v38, s[38:39]
	s_nop 0
	global_load_dwordx4 v[4:7], v38, s[38:39] offset:16
	v_and_b32_e32 v41, 0xffff0000, v42
	v_pk_mul_f32 v[10:11], v[40:41], v[40:41]
	v_lshlrev_b32_e32 v8, 16, v43
	v_and_b32_e32 v9, 0xffff0000, v43
	v_add_f32_e32 v10, v28, v10
	v_pk_mul_f32 v[26:27], v[8:9], v[8:9]
	v_add_f32_e32 v10, v10, v11
	v_add_f32_e32 v10, v10, v26
	v_add_f32_e32 v10, v10, v27
	s_nop 1
	v_mov_b32_dpp v11, v10 quad_perm:[1,0,3,2] row_mask:0xf bank_mask:0xf
	s_waitcnt lgkmcnt(0)
	v_add_f32_e32 v10, v10, v11
	s_nop 1
	v_mov_b32_dpp v11, v10 quad_perm:[2,3,0,1] row_mask:0xf bank_mask:0xf
	s_waitcnt lgkmcnt(0)
	v_add_f32_e32 v10, v10, v11
	s_nop 1
	v_mov_b32_dpp v11, v10 row_half_mirror row_mask:0xf bank_mask:0xf
	s_waitcnt lgkmcnt(0)
	v_add_f32_e32 v10, v10, v11
	s_nop 1
	v_mov_b32_dpp v11, v10 row_mirror row_mask:0xf bank_mask:0xf
	s_waitcnt lgkmcnt(0)
	v_add_f32_e32 v10, v10, v11
	ds_bpermute_b32 v11, v36, v10
	s_waitcnt lgkmcnt(0)
	v_add_f32_e32 v10, v10, v11
	ds_bpermute_b32 v11, v37, v10
	s_waitcnt lgkmcnt(0)
	v_add_f32_e32 v10, v10, v11
	v_fmamk_f32 v10, v10, 0x3b000000, v196
	v_mul_f32_e32 v11, 0x4b800000, v10
	v_cmp_gt_f32_e32 vcc, s78, v10
	s_nop 1
	v_cndmask_b32_e32 v10, v10, v11, vcc
	v_rsq_f32_e32 v10, v10
	s_nop 0
	v_mul_f32_e32 v11, 0x45800000, v10
	v_cndmask_b32_e32 v10, v10, v11, vcc
	v_mul_f32_e32 v11, v10, v58
	v_mul_f32_e32 v26, v10, v59
	v_mul_f32_e32 v27, v10, v60
	v_mul_f32_e32 v28, v10, v61
	v_mul_f32_e32 v29, v10, v40
	v_mul_f32_e32 v40, v10, v41
	v_mul_f32_e32 v8, v10, v8
	v_mul_f32_e32 v9, v10, v9
	s_waitcnt vmcnt(1)
	v_mul_f32_e32 v0, v0, v11
	v_mul_f32_e32 v1, v1, v26
	v_mul_f32_e32 v2, v2, v27
	v_mul_f32_e32 v3, v3, v28
	s_waitcnt vmcnt(0)
	v_mul_f32_e32 v4, v4, v29
	v_mul_f32_e32 v5, v5, v40
	v_mul_f32_e32 v6, v6, v8
	v_mul_f32_e32 v7, v7, v9
	v_cvt_pk_bf16_f32 v0, v0, v1
	v_cvt_pk_bf16_f32 v1, v2, v3
	v_cvt_pk_bf16_f32 v2, v4, v5
	v_cvt_pk_bf16_f32 v3, v6, v7
	global_store_dwordx4 v[30:31], v[0:3], off offset:3072
	s_cbranch_scc1 .LBB0_1365

; __device__ __forceinline__ float bflo(unsigned w) { return __uint_as_float(w << 16); }
; __device__ __forceinline__ float bfhi(unsigned w) { return __uint_as_float(w & 0xffff0000u); }
; __device__ __forceinline__ float wave_sum(float v, int lane) {
; #pragma unroll
;     for (int o = 1; o < 64; o <<= 1) v += __uint_as_float((unsigned)__builtin_amdgcn_ds_bpermute((lane ^ o) << 2, (int)__float_as_uint(v)));
;     return v;
; }
; __global__ void __launch_bounds__(512) mega_fwd(Params P) {
;     ...
;       for (int m = gw; m < MTOK; m += NGW) { const u32x2* xb = (const u32x2*)(XN + (size_t)m * DM) + lane; f32x4* xr = (f32x4*)(X + (size_t)m * DM) + lane; f32x4 v[8]; float s = 0.f;
; #pragma unroll
;         for (int j = 0; j < 8; ++j) { const u32x2 w = xb[64 * j]; v[j] = (f32x4){bflo(w.x), bfhi(w.x), bflo(w.y), bfhi(w.y)}; s += (v[j].x * v[j].x + v[j].y * v[j].y) + (v[j].z * v[j].z + v[j].w * v[j].w); }
;         const float rs = rsqrtf(wave_sum(s, lane) * (1.f / DM) + EPS); const f32x4* gr = (const f32x4*)gf + lane;
.LBB0_1808:
	global_load_dwordx2 v[26:27], v[16:17], off offset:-3584
	global_load_dwordx2 v[28:29], v[16:17], off offset:-3072
	global_load_dwordx2 v[30:31], v[16:17], off offset:-2560
	global_load_dwordx2 v[32:33], v[16:17], off offset:-2048
	global_load_dwordx2 v[34:35], v[16:17], off offset:-1536
	global_load_dwordx2 v[36:37], v[16:17], off offset:-1024
	global_load_dwordx2 v[38:39], v[16:17], off offset:-512
	global_load_dwordx2 v[40:41], v[16:17], off
	global_load_dwordx4 v[0:3], v[4:5], off
	v_add_co_u32_e32 v42, vcc, s3, v14
	s_add_i32 s0, s0, s2
	s_nop 0
	v_addc_co_u32_e32 v43, vcc, -1, v15, vcc
	v_lshl_add_u64 v[16:17], v[16:17], 0, s[6:7]
	s_cmp_lt_i32 s0, 0xa000
	s_waitcnt vmcnt(8)
	v_lshlrev_b32_e32 v44, 16, v26
	v_and_b32_e32 v45, 0xffff0000, v26
	v_lshlrev_b32_e32 v26, 16, v27
	v_and_b32_e32 v27, 0xffff0000, v27
	s_waitcnt vmcnt(7)
	v_lshlrev_b32_e32 v46, 16, v28
	v_and_b32_e32 v47, 0xffff0000, v28
	v_lshlrev_b32_e32 v28, 16, v29
	v_and_b32_e32 v29, 0xffff0000, v29
	s_waitcnt vmcnt(6)
	v_lshlrev_b32_e32 v48, 16, v30
	v_and_b32_e32 v49, 0xffff0000, v30
	v_lshlrev_b32_e32 v30, 16, v31
	v_and_b32_e32 v31, 0xffff0000, v31
	v_mov_b32_e32 v62, v45
	v_mov_b32_e32 v63, v47
	v_mov_b32_e32 v66, v27
	v_mov_b32_e32 v67, v29
	v_mov_b32_e32 v60, v44
	v_mov_b32_e32 v61, v46
	v_mov_b32_e32 v64, v26
	v_mov_b32_e32 v65, v28
	v_mov_b32_e32 v70, v49
	v_mov_b32_e32 v71, v31
	v_pk_mul_f32 v[62:63], v[62:63], v[62:63]
	v_pk_mul_f32 v[66:67], v[66:67], v[66:67]
	s_waitcnt vmcnt(5)
	v_lshlrev_b32_e32 v50, 16, v32
	v_and_b32_e32 v51, 0xffff0000, v32
	v_lshlrev_b32_e32 v32, 16, v33
	v_and_b32_e32 v33, 0xffff0000, v33
	v_mov_b32_e32 v68, v48
	v_mov_b32_e32 v69, v30
	v_pk_mul_f32 v[70:71], v[70:71], v[70:71]
	v_pk_fma_f32 v[60:61], v[60:61], v[60:61], v[62:63]
	v_pk_fma_f32 v[62:63], v[64:65], v[64:65], v[66:67]
	s_waitcnt vmcnt(4)
	v_lshlrev_b32_e32 v52, 16, v34
	v_and_b32_e32 v53, 0xffff0000, v34
	v_lshlrev_b32_e32 v34, 16, v35
	v_and_b32_e32 v35, 0xffff0000, v35
	v_mul_f32_e32 v72, v51, v51
	v_mul_f32_e32 v74, v33, v33
	v_pk_fma_f32 v[64:65], v[68:69], v[68:69], v[70:71]
	v_pk_add_f32 v[60:61], v[60:61], v[62:63]
	s_waitcnt vmcnt(3)
	v_lshlrev_b32_e32 v54, 16, v36
	v_and_b32_e32 v55, 0xffff0000, v36
	v_lshlrev_b32_e32 v36, 16, v37
	v_and_b32_e32 v37, 0xffff0000, v37
	v_pk_mul_f32 v[76:77], v[52:53], v[52:53]
	v_pk_mul_f32 v[78:79], v[34:35], v[34:35]
	v_pk_fma_f32 v[72:73], v[50:51], v[50:51], v[72:73] op_sel_hi:[1,1,0]
	v_pk_fma_f32 v[74:75], v[32:33], v[32:33], v[74:75] op_sel_hi:[1,1,0]
	v_pk_add_f32 v[62:63], v[64:65], v[64:65] op_sel:[0,1] op_sel_hi:[1,0]
	v_pk_add_f32 v[60:61], v[60:61], v[60:61] op_sel:[0,1] op_sel_hi:[1,0]
	v_mov_b32_e32 v82, v55
	v_mov_b32_e32 v83, v37
	v_mov_b32_e32 v73, v78
	v_mov_b32_e32 v75, v79
	v_mov_b32_e32 v63, v77
	v_mov_b32_e32 v61, v76
	s_waitcnt vmcnt(2)
	v_lshlrev_b32_e32 v56, 16, v38
	v_and_b32_e32 v57, 0xffff0000, v38
	v_lshlrev_b32_e32 v38, 16, v39
	v_and_b32_e32 v39, 0xffff0000, v39
	v_mov_b32_e32 v80, v54
	v_mov_b32_e32 v81, v36
	v_pk_mul_f32 v[82:83], v[82:83], v[82:83]
	v_pk_add_f32 v[64:65], v[72:73], v[74:75]
	v_pk_add_f32 v[60:61], v[60:61], v[62:63]
	s_waitcnt vmcnt(1)
	v_lshlrev_b32_e32 v58, 16, v40
	v_and_b32_e32 v59, 0xffff0000, v40
	v_lshlrev_b32_e32 v40, 16, v41
	v_and_b32_e32 v41, 0xffff0000, v41
	v_mul_f32_e32 v84, v57, v57
	v_mul_f32_e32 v86, v39, v39
	v_pk_fma_f32 v[66:67], v[80:81], v[80:81], v[82:83]
	v_pk_add_f32 v[60:61], v[60:61], v[64:65]
	v_pk_mul_f32 v[88:89], v[58:59], v[58:59]
	v_pk_mul_f32 v[90:91], v[40:41], v[40:41]
	v_pk_fma_f32 v[84:85], v[56:57], v[56:57], v[84:85] op_sel_hi:[1,1,0]
	v_pk_fma_f32 v[86:87], v[38:39], v[38:39], v[86:87] op_sel_hi:[1,1,0]
	v_pk_add_f32 v[66:67], v[66:67], v[66:67] op_sel:[0,1] op_sel_hi:[1,0]
	v_pk_add_f32 v[60:61], v[60:61], v[60:61] op_sel:[0,1] op_sel_hi:[1,0]
	v_mov_b32_e32 v85, v90
	v_mov_b32_e32 v87, v91
	v_mov_b32_e32 v67, v89
	v_mov_b32_e32 v61, v88
	v_pk_add_f32 v[68:69], v[84:85], v[86:87]
	v_pk_add_f32 v[60:61], v[60:61], v[66:67]
	s_nop 0
	v_pk_add_f32 v[60:61], v[60:61], v[68:69]
	s_nop 0
	v_add_f32_e32 v25, v60, v61
	s_nop 1
	v_mov_b32_dpp v60, v25 quad_perm:[1,0,3,2] row_mask:0xf bank_mask:0xf
	s_waitcnt lgkmcnt(0)
; __global__ void __launch_bounds__(512) mega_fwd(Params P) {
;     ...
;         const float rs = rsqrtf(wave_sum(s, lane) * (1.f / DM) + EPS); const f32x4* gr = (const f32x4*)gf + lane;
; #pragma unroll
;         for (int j = 0; j < 8; ++j) { const f32x4 gv = gr[64 * j]; xr[64 * j] = (f32x4){v[j].x * rs * gv.x, v[j].y * rs * gv.y, v[j].z * rs * gv.z, v[j].w * rs * gv.w}; } } }
	v_add_f32_e32 v25, v25, v60
	s_nop 1
	v_mov_b32_dpp v60, v25 quad_perm:[2,3,0,1] row_mask:0xf bank_mask:0xf
	s_waitcnt lgkmcnt(0)
	v_add_f32_e32 v25, v25, v60
	s_nop 1
	v_mov_b32_dpp v60, v25 row_half_mirror row_mask:0xf bank_mask:0xf
	s_waitcnt lgkmcnt(0)
	v_add_f32_e32 v25, v25, v60
	s_nop 1
	v_mov_b32_dpp v60, v25 row_mirror row_mask:0xf bank_mask:0xf
	s_waitcnt lgkmcnt(0)
	v_add_f32_e32 v25, v25, v60
	ds_bpermute_b32 v60, v22, v25
	s_waitcnt lgkmcnt(0)
	v_add_f32_e32 v25, v25, v60
	ds_bpermute_b32 v60, v23, v25
	s_waitcnt lgkmcnt(0)
	v_add_f32_e32 v25, v25, v60
	v_fmamk_f32 v25, v25, 0x3a000000, v24
	v_mul_f32_e32 v60, 0x4b800000, v25
	v_cmp_gt_f32_e32 vcc, s1, v25
	s_nop 1
	v_cndmask_b32_e32 v25, v25, v60, vcc
	v_rsq_f32_e32 v25, v25
	s_nop 0
	v_mul_f32_e32 v60, 0x45800000, v25
	v_cndmask_b32_e32 v60, v25, v60, vcc
	v_pk_mul_f32 v[44:45], v[60:61], v[44:45] op_sel_hi:[0,1]
	v_pk_mul_f32 v[26:27], v[60:61], v[26:27] op_sel_hi:[0,1]
	s_waitcnt vmcnt(0)
	v_pk_mul_f32 v[0:1], v[0:1], v[44:45]
	v_pk_mul_f32 v[2:3], v[2:3], v[26:27]
	global_store_dwordx4 v[42:43], v[0:3], off offset:-3072
	global_load_dwordx4 v[0:3], v[4:5], off offset:1024
	v_pk_mul_f32 v[26:27], v[60:61], v[46:47] op_sel_hi:[0,1]
	v_pk_mul_f32 v[28:29], v[60:61], v[28:29] op_sel_hi:[0,1]
	s_waitcnt vmcnt(0)
	v_pk_mul_f32 v[0:1], v[0:1], v[26:27]
	v_pk_mul_f32 v[2:3], v[2:3], v[28:29]
	global_store_dwordx4 v[42:43], v[0:3], off offset:-2048
	global_load_dwordx4 v[0:3], v[4:5], off offset:2048
	v_pk_mul_f32 v[26:27], v[60:61], v[48:49] op_sel_hi:[0,1]
	v_pk_mul_f32 v[28:29], v[60:61], v[30:31] op_sel_hi:[0,1]
	s_waitcnt vmcnt(0)
	v_pk_mul_f32 v[0:1], v[0:1], v[26:27]
	v_pk_mul_f32 v[2:3], v[2:3], v[28:29]
	global_store_dwordx4 v[42:43], v[0:3], off offset:-1024
	global_load_dwordx4 v[0:3], v[4:5], off offset:3072
	v_pk_mul_f32 v[26:27], v[60:61], v[32:33] op_sel_hi:[0,1]
	v_pk_mul_f32 v[28:29], v[60:61], v[50:51] op_sel_hi:[0,1]
	s_waitcnt vmcnt(0)
	v_pk_mul_f32 v[0:1], v[0:1], v[28:29]
	v_pk_mul_f32 v[2:3], v[2:3], v[26:27]
	global_store_dwordx4 v[14:15], v[0:3], off offset:-4096
	global_load_dwordx4 v[0:3], v[6:7], off
	v_pk_mul_f32 v[26:27], v[60:61], v[34:35] op_sel_hi:[0,1]
	v_pk_mul_f32 v[28:29], v[60:61], v[52:53] op_sel_hi:[0,1]
	s_waitcnt vmcnt(0)
	v_pk_mul_f32 v[0:1], v[0:1], v[28:29]
	v_pk_mul_f32 v[2:3], v[2:3], v[26:27]
	global_store_dwordx4 v[14:15], v[0:3], off offset:-3072
	global_load_dwordx4 v[0:3], v[8:9], off
	v_pk_mul_f32 v[26:27], v[60:61], v[54:55] op_sel_hi:[0,1]
	v_pk_mul_f32 v[28:29], v[60:61], v[36:37] op_sel_hi:[0,1]
	s_waitcnt vmcnt(0)
	v_pk_mul_f32 v[0:1], v[0:1], v[26:27]
	v_pk_mul_f32 v[2:3], v[2:3], v[28:29]
	global_store_dwordx4 v[14:15], v[0:3], off offset:-2048
	global_load_dwordx4 v[0:3], v[10:11], off
	v_pk_mul_f32 v[26:27], v[60:61], v[38:39] op_sel_hi:[0,1]
	v_pk_mul_f32 v[28:29], v[60:61], v[56:57] op_sel_hi:[0,1]
	s_waitcnt vmcnt(0)
	v_pk_mul_f32 v[0:1], v[0:1], v[28:29]
	v_pk_mul_f32 v[2:3], v[2:3], v[26:27]
	global_store_dwordx4 v[14:15], v[0:3], off offset:-1024
	global_load_dwordx4 v[0:3], v[12:13], off
	v_pk_mul_f32 v[26:27], v[60:61], v[40:41] op_sel_hi:[0,1]
	v_pk_mul_f32 v[28:29], v[60:61], v[58:59] op_sel_hi:[0,1]
	s_waitcnt vmcnt(0)
	v_pk_mul_f32 v[0:1], v[0:1], v[28:29]
	v_pk_mul_f32 v[2:3], v[2:3], v[26:27]
	global_store_dwordx4 v[14:15], v[0:3], off
	v_lshl_add_u64 v[14:15], v[14:15], 0, s[4:5]
	s_cbranch_scc1 .LBB0_1808
